# DeltaNet chunk: fragment reads of the W*S/Q*S and K*K^T/Q*K^T MFMA sections hoisted (3 k-steps in flight) using free VGPR quads
# baseline (speedup 1.0000x reference)
.LBB0_541:
	s_or_b64 exec, exec, s[2:3]
	s_sub_i32 s14, s11, 32
	s_add_i32 s15, s25, 32
	v_lshlrev_b32_e32 v152, 5, v168
	s_and_b64 s[2:3], s[12:13], exec
	v_or_b32_e32 v153, v152, v165
	v_add_u32_e32 v154, 16, v170
	s_cselect_b32 s2, s14, s15
	v_mad_u64_u32 v[194:195], s[14:15], v153, s69, v[154:155]
	s_waitcnt lgkmcnt(0)
	s_barrier
	ds_read_b128 v[60:63], v172 offset:49664
	ds_read_b128 v[64:67], v172
	ds_read_b128 v[156:159], v194 offset:17408
	ds_read_b128 v[186:189], v194 offset:21760
	ds_read_b128 v[220:223], v172 offset:49728
	ds_read_b128 v[224:227], v172 offset:64
	ds_read_b128 v[228:231], v194 offset:17472
	ds_read_b128 v[232:235], v194 offset:21824
	ds_read_b128 v[236:239], v172 offset:49792
	ds_read_b128 v[240:243], v172 offset:128
	ds_read_b128 v[244:247], v194 offset:17536
	ds_read_b128 v[248:251], v194 offset:21888
	s_waitcnt lgkmcnt(9)
	v_mfma_f32_16x16x32_bf16 v[182:185], v[60:63], v[156:159], 0
	v_mfma_f32_16x16x32_bf16 v[156:159], v[64:67], v[156:159], 0
	v_mul_u32_u24_e32 v167, 0x104, v169
	v_lshl_add_u32 v168, v169, 1, s83
	v_lshl_add_u32 v155, v0, 1, 16
	v_lshlrev_b32_e32 v0, 1, v165
	v_cmp_gt_u32_e32 vcc, s61, v166
	s_waitcnt lgkmcnt(8)
	v_mfma_f32_16x16x32_bf16 v[60:63], v[60:63], v[186:189], 0
	v_mfma_f32_16x16x32_bf16 v[64:67], v[64:67], v[186:189], 0
	ds_read_b128 v[190:193], v172 offset:49856
	ds_read_b128 v[200:203], v172 offset:192
	ds_read_b128 v[186:189], v194 offset:17600
	v_lshl_or_b32 v109, v109, 5, v165
	s_add_i32 s2, s2, s96
	s_add_i32 s11, s11, 32
	s_sub_i32 s25, s25, 32
	s_cmp_eq_u32 s8, s10
	s_waitcnt lgkmcnt(7)
	v_mfma_f32_16x16x32_bf16 v[182:185], v[220:223], v[228:231], v[182:185]
	v_mfma_f32_16x16x32_bf16 v[156:159], v[224:227], v[228:231], v[156:159]
	v_mfma_f32_16x16x32_bf16 v[60:63], v[220:223], v[232:235], v[60:63]
	v_mfma_f32_16x16x32_bf16 v[64:67], v[224:227], v[232:235], v[64:67]
	ds_read_b128 v[220:223], v194 offset:21952
	v_lshlrev_b32_e32 v172, 2, v153
	v_add3_u32 v167, 16, v167, v172
	v_add_u32_e32 v167, 0xe400, v167
	v_mul_lo_u32 v153, v153, s82
	v_add_u32_e32 v181, v168, v153
	s_waitcnt lgkmcnt(4)
	v_mfma_f32_16x16x32_bf16 v[182:185], v[236:239], v[244:247], v[182:185]
	v_mfma_f32_16x16x32_bf16 v[156:159], v[240:243], v[244:247], v[156:159]
	v_mfma_f32_16x16x32_bf16 v[60:63], v[236:239], v[248:251], v[60:63]
	v_mfma_f32_16x16x32_bf16 v[64:67], v[240:243], v[248:251], v[64:67]
	s_waitcnt lgkmcnt(0)
	v_mfma_f32_16x16x32_bf16 v[182:185], v[190:193], v[186:189], v[182:185]
	v_mfma_f32_16x16x32_bf16 v[156:159], v[200:203], v[186:189], v[156:159]
	v_mfma_f32_16x16x32_bf16 v[60:63], v[190:193], v[220:223], v[60:63]
	v_mfma_f32_16x16x32_bf16 v[64:67], v[200:203], v[220:223], v[64:67]
	ds_read2_b32 v[186:187], v167 offset1:16
	s_waitcnt lgkmcnt(0)
	v_sub_f32_e32 v172, v186, v182
	ds_read2_b32 v[190:191], v167 offset0:65 offset1:81
	s_nop 2
	v_sub_f32_e32 v60, v187, v60
	v_add_u32_e32 v192, 0x500, v153
	v_cvt_pk_bf16_f32 v60, v60, s0
	v_add_u32_e32 v168, v168, v192
	ds_write_b16 v168, v60
	v_mul_u32_u24_e32 v60, 0x50, v169
	v_cvt_pk_bf16_f32 v172, v172, s0
	v_add3_u32 v155, v155, v0, v60
	s_waitcnt lgkmcnt(1)
	v_sub_f32_e32 v60, v190, v183
	v_add_u32_e32 v153, s83, v153
	v_lshlrev_b32_e32 v168, 1, v176
	ds_write_b16 v181, v172
	ds_write_b16 v155, v180 offset:45056
	v_cvt_pk_bf16_f32 v60, v60, s0
	v_add_u32_e32 v176, v153, v168
	ds_read_b128 v[180:183], v173 offset:384
	ds_read_b128 v[186:189], v173 offset:128
	ds_write_b16 v176, v60
	v_sub_f32_e32 v60, v191, v61
	v_add_u32_e32 v176, s83, v192
	v_cvt_pk_bf16_f32 v60, v60, s0
	v_add_u32_e32 v61, v176, v168
	ds_write_b16 v61, v60
	ds_write_b16 v155, v178 offset:45136
	ds_read2_b32 v[60:61], v167 offset0:130 offset1:146
	v_lshlrev_b32_e32 v168, 1, v175
	v_add_u32_e32 v175, v153, v168
	s_waitcnt lgkmcnt(4)
	v_pk_mul_f32 v[172:173], v[180:181], v[186:187]
	s_waitcnt lgkmcnt(0)
	v_sub_f32_e32 v60, v60, v184
	v_cvt_pk_bf16_f32 v60, v60, s0
	ds_write_b16 v175, v60
	v_sub_f32_e32 v60, v61, v62
	v_cvt_pk_bf16_f32 v60, v60, s0
	v_add_u32_e32 v61, v176, v168
	ds_write_b16 v61, v60
	ds_write_b16 v155, v179 offset:45216
	ds_read2_b32 v[60:61], v167 offset0:195 offset1:211
	v_lshlrev_b32_e32 v62, 1, v174
	v_add_u32_e32 v153, v153, v62
	v_pk_mul_f32 v[156:157], v[156:157], v[172:173]
	v_pk_mul_f32 v[64:65], v[64:65], v[172:173]
	s_waitcnt lgkmcnt(0)
	v_sub_f32_e32 v60, v60, v185
	v_cvt_pk_bf16_f32 v60, v60, s0
	ds_write_b16 v153, v60
	v_sub_f32_e32 v60, v61, v63
	v_cvt_pk_bf16_f32 v60, v60, s0
	v_add_u32_e32 v61, v176, v62
	ds_write_b16 v61, v60
	ds_write_b16 v155, v177 offset:45296
	v_mov_b32_e32 v60, s71
	s_waitcnt lgkmcnt(0)
	s_barrier
	ds_read_b32 v168, v60
	v_mad_u32_u24 v60, v171, s82, v154
	ds_read_b128 v[172:175], v60 offset:45056
	v_mul_u32_u24_e32 v60, 0x50, v165
	v_pk_mul_f32 v[178:179], v[182:183], v[188:189]
	v_add3_u32 v60, s83, v170, v60
	v_pk_mul_f32 v[158:159], v[158:159], v[178:179]
	v_pk_mul_f32 v[66:67], v[66:67], v[178:179]
	ds_read_b128 v[176:179], v60
	ds_read_b128 v[180:183], v60 offset:1280
	ds_read_b128 v[184:187], v60 offset:2560
	ds_read_b128 v[188:191], v60 offset:3840
	s_waitcnt lgkmcnt(5)
	v_pk_mul_f32 v[18:19], v[18:19], v[168:169] op_sel_hi:[1,0]
	v_pk_mul_f32 v[16:17], v[16:17], v[168:169] op_sel_hi:[1,0]
	v_pk_mul_f32 v[14:15], v[14:15], v[168:169] op_sel_hi:[1,0]
	s_waitcnt lgkmcnt(1)
	v_cndmask_b32_e32 v63, v187, v179, vcc
	v_cndmask_b32_e32 v62, v186, v178, vcc
	v_cndmask_b32_e32 v61, v185, v177, vcc
	v_cndmask_b32_e32 v60, v184, v176, vcc
	v_pk_mul_f32 v[12:13], v[12:13], v[168:169] op_sel_hi:[1,0]
	v_pk_mul_f32 v[6:7], v[6:7], v[168:169] op_sel_hi:[1,0]
	v_mfma_f32_16x16x32_bf16 v[60:63], v[172:175], v[60:63], v[156:159]
	v_mul_f32_e64 v4, v4, v168
	v_mul_f32_e64 v5, v5, v168
	v_pk_mul_f32 v[10:11], v[10:11], v[168:169] op_sel_hi:[1,0]
	v_pk_mul_f32 v[8:9], v[8:9], v[168:169] op_sel_hi:[1,0]
	s_waitcnt lgkmcnt(0)
	v_cndmask_b32_e32 v159, v191, v183, vcc
	v_cndmask_b32_e32 v158, v190, v182, vcc
	v_cndmask_b32_e32 v157, v189, v181, vcc
	v_cndmask_b32_e32 v156, v188, v180, vcc
	v_pk_mul_f32 v[26:27], v[26:27], v[168:169] op_sel_hi:[1,0]
	v_pk_mul_f32 v[24:25], v[24:25], v[168:169] op_sel_hi:[1,0]
	v_mfma_f32_16x16x32_bf16 v[64:67], v[172:175], v[156:159], v[64:67]
	v_mad_u64_u32 v[158:159], s[14:15], v109, s82, v[154:155]
	ds_read_b128 v[154:157], v158 offset:34816
	s_waitcnt lgkmcnt(0)
	v_mfma_f32_16x16x32_bf16 v[16:19], v[154:157], v[176:179], v[16:19]
	v_mul_f32_e64 v22, v22, v168
	v_mul_f32_e64 v23, v23, v168
	v_pk_mul_f32 v[20:21], v[20:21], v[168:169] op_sel_hi:[1,0]
	v_pk_mul_f32 v[34:35], v[34:35], v[168:169] op_sel_hi:[1,0]
	v_mfma_f32_16x16x32_bf16 v[12:15], v[154:157], v[180:183], v[12:15]
	v_mul_f32_e64 v32, v32, v168
	v_mul_f32_e64 v33, v33, v168
	v_pk_mul_f32 v[30:31], v[30:31], v[168:169] op_sel_hi:[1,0]
	v_pk_mul_f32 v[28:29], v[28:29], v[168:169] op_sel_hi:[1,0]
	v_mfma_f32_16x16x32_bf16 v[4:7], v[154:157], v[184:187], v[4:7]
	v_mov_b32_e32 v109, s2
	v_ashrrev_i32_e32 v153, 31, v152
	v_lshlrev_b64 v[152:153], 1, v[152:153]
	v_mfma_f32_16x16x32_bf16 v[8:11], v[154:157], v[188:191], v[8:11]
	ds_read_b128 v[154:157], v158 offset:36096
	v_cvt_pk_bf16_f32 v60, v60, s0
	s_waitcnt lgkmcnt(0)
	v_mfma_f32_16x16x32_bf16 v[24:27], v[154:157], v[176:179], v[24:27]
	v_mfma_f32_16x16x32_bf16 v[20:23], v[154:157], v[180:183], v[20:23]
	v_mfma_f32_16x16x32_bf16 v[32:35], v[154:157], v[184:187], v[32:35]
	v_mfma_f32_16x16x32_bf16 v[28:31], v[154:157], v[188:191], v[28:31]
	v_mad_i32_i24 v154, v169, s97, v109
	v_ashrrev_i32_e32 v155, 31, v154
	v_lshlrev_b64 v[156:157], 12, v[154:155]
	v_lshl_add_u64 v[156:157], s[58:59], 0, v[156:157]
	v_lshl_add_u64 v[156:157], v[156:157], 0, v[0:1]
	v_lshl_add_u64 v[156:157], v[156:157], 0, v[152:153]
	v_add_u32_e32 v154, s97, v154
	global_store_short v[156:157], v60, off offset:2048
	v_cvt_pk_bf16_f32 v60, v64, s0
	v_ashrrev_i32_e32 v155, 31, v154
	global_store_short v[156:157], v60, off offset:2080
	v_lshlrev_b64 v[156:157], 12, v[154:155]
	v_lshl_add_u64 v[156:157], s[58:59], 0, v[156:157]
	v_lshl_add_u64 v[156:157], v[156:157], 0, v[0:1]
	v_cvt_pk_bf16_f32 v64, v61, s0
	v_lshl_add_u64 v[60:61], v[156:157], 0, v[152:153]
	global_store_short v[60:61], v64, off offset:2048
	v_cvt_pk_bf16_f32 v64, v65, s0
	global_store_short v[60:61], v64, off offset:2080
	v_add_u32_e32 v60, s97, v154
	v_ashrrev_i32_e32 v61, 31, v60
	v_lshlrev_b64 v[64:65], 12, v[60:61]
	v_lshl_add_u64 v[64:65], s[58:59], 0, v[64:65]
	v_lshl_add_u64 v[64:65], v[64:65], 0, v[0:1]
	v_cvt_pk_bf16_f32 v61, v62, s0
	v_lshl_add_u64 v[64:65], v[64:65], 0, v[152:153]
	global_store_short v[64:65], v61, off offset:2048
	v_cvt_pk_bf16_f32 v61, v66, s0
	v_add_u32_e32 v60, s97, v60
	global_store_short v[64:65], v61, off offset:2080
	v_ashrrev_i32_e32 v61, 31, v60
	v_lshlrev_b64 v[60:61], 12, v[60:61]
	v_lshl_add_u64 v[60:61], s[58:59], 0, v[60:61]
	v_lshl_add_u64 v[60:61], v[60:61], 0, v[0:1]
	v_cvt_pk_bf16_f32 v0, v63, s0
	v_lshl_add_u64 v[60:61], v[60:61], 0, v[152:153]
	global_store_short v[60:61], v0, off offset:2048
	v_cvt_pk_bf16_f32 v0, v67, s0
	global_store_short v[60:61], v0, off offset:2080
	s_cbranch_scc1 .LBB0_606

.LBB0_582:
	v_lshlrev_b32_e32 v0, 4, v109
	v_and_b32_e32 v169, 16, v0
	v_or_b32_e32 v171, v169, v165
	v_mul_u32_u24_e32 v0, 0x88, v171
	v_lshlrev_b32_e32 v0, 1, v0
	v_lshlrev_b32_e32 v170, 1, v152
	v_add3_u32 v172, 16, v0, v170
	v_lshlrev_b32_e32 v0, 4, v168
	v_or_b32_e32 v155, v0, v165
	v_mul_lo_u32 v60, v155, s69
	v_add3_u32 v152, 16, v60, v170
	ds_read_b128 v[60:63], v172
	ds_read_b128 v[64:67], v172 offset:8704
	ds_read_b128 v[156:159], v152 offset:8704
	ds_read_b128 v[220:223], v172 offset:64
	ds_read_b128 v[224:227], v172 offset:8768
	ds_read_b128 v[228:231], v152 offset:8768
	ds_read_b128 v[232:235], v172 offset:128
	ds_read_b128 v[236:239], v172 offset:8832
	ds_read_b128 v[240:243], v152 offset:8832
	ds_read_b128 v[244:247], v172 offset:192
	ds_read_b128 v[248:251], v172 offset:8896
	ds_read_b128 v[174:177], v152 offset:8896
	v_lshl_or_b32 v169, v154, 2, v169
	s_waitcnt lgkmcnt(9)
	v_mfma_f32_16x16x32_bf16 v[64:67], v[64:67], v[156:159], 0
	v_lshl_add_u32 v173, v169, 2, s70
	v_cmp_lt_i32_e32 vcc, v155, v169
	v_mfma_f32_16x16x32_bf16 v[60:63], v[60:63], v[156:159], 0
	s_waitcnt lgkmcnt(6)
	v_mfma_f32_16x16x32_bf16 v[64:67], v[224:227], v[228:231], v[64:67]
	v_mfma_f32_16x16x32_bf16 v[60:63], v[220:223], v[228:231], v[60:63]
	s_waitcnt lgkmcnt(3)
	v_mfma_f32_16x16x32_bf16 v[64:67], v[236:239], v[240:243], v[64:67]
	v_mfma_f32_16x16x32_bf16 v[60:63], v[232:235], v[240:243], v[60:63]
	v_lshl_add_u32 v152, v155, 2, s70
	ds_read2st64_b32 v[152:153], v152 offset1:2
	ds_read_b32 v154, v173
	s_waitcnt lgkmcnt(2)
	v_mfma_f32_16x16x32_bf16 v[64:67], v[248:251], v[174:177], v[64:67]
	s_waitcnt lgkmcnt(0)
	v_sub_f32_e32 v154, v154, v152
	v_mul_f32_e32 v154, 0x3fb8aa3b, v154
	v_mfma_f32_16x16x32_bf16 v[60:63], v[244:247], v[174:177], v[60:63]
	v_exp_f32_e32 v156, v154
	v_mov_b32_e32 v154, 0
	v_mov_b32_e32 v157, 0
	s_and_saveexec_b64 s[2:3], vcc
	s_cbranch_execz .LBB0_584
	ds_read2st64_b32 v[158:159], v173 offset0:1 offset1:2
	s_waitcnt lgkmcnt(0)
	v_mul_f32_e32 v157, v158, v159
	v_mul_f32_e32 v157, v153, v157
	v_mul_f32_e32 v157, v156, v157
	v_mul_f32_e32 v157, v64, v157
